# GLA main: hoist 16 ds_read_u16 Q/K reads to top of decay segment; exact vmcnt at chunk top so store acks are not waited
# baseline (speedup 1.0000x reference)
.LBB0_633:
	s_or_b64 exec, exec, s[2:3]
	v_cmp_lt_i32_e32 vcc, v246, v239
	s_movk_i32 s2, 0x80
	v_lshl_add_u32 v11, v4, 8, s92
	v_cndmask_b32_e32 v4, v237, v246, vcc
	v_cmp_gt_u32_e64 s[40:41], s2, v195
	s_movk_i32 s2, 0x210
	v_lshl_add_u32 v10, v3, 7, s92
	v_lshlrev_b32_e32 v124, 2, v4
	v_lshlrev_b32_e32 v4, 2, v190
	v_add_u32_e32 v127, s79, v3
	v_mul_lo_u32 v3, v111, s2
	v_lshlrev_b32_e32 v21, 6, v2
	v_lshl_or_b32 v18, v196, 3, v4
	v_add3_u32 v128, s92, v3, v21
	v_lshlrev_b32_e32 v3, 4, v195
	v_and_b32_e32 v21, 0xffffffe0, v3
	v_and_b32_e32 v22, 16, v3
	v_or_b32_e32 v3, 1, v18
	v_cmp_gt_i32_e64 s[46:47], v197, v3
	v_or_b32_e32 v3, 2, v18
	v_ashrrev_i32_e32 v8, 7, v195
	v_cmp_gt_i32_e64 s[48:49], v197, v3
	v_or_b32_e32 v3, 3, v18
	v_lshl_add_u32 v12, v5, 8, s92
	v_lshl_or_b32 v5, v8, 4, v4
	s_movk_i32 s11, 0x50
	s_movk_i32 s3, 0x90
	v_cmp_gt_i32_e64 s[50:51], v197, v3
	v_or_b32_e32 v3, 8, v4
	v_mov_b32_e32 v9, s92
	v_lshlrev_b32_e32 v130, 7, v5
	v_mul_lo_u32 v23, v5, s3
	v_cmp_gt_i32_e64 s[44:45], v197, v18
	v_mul_lo_u32 v31, v18, s11
	v_lshlrev_b32_e32 v18, 1, v3
	v_lshlrev_b32_e32 v5, 2, v72
	v_mul_u32_u24_e32 v3, 0x210, v3
	v_cmp_eq_u32_e32 vcc, 2, v196
	v_mad_u32_u24 v17, v197, s3, v9
	v_add3_u32 v132, s92, v3, v5
	v_cndmask_b32_e64 v3, 12, 8, vcc
	v_cmp_eq_u32_e64 s[2:3], 1, v196
	v_cmp_gt_u32_e64 s[54:55], 64, v195
	v_cmp_eq_u32_e64 s[38:39], 0, v190
	v_cndmask_b32_e64 v3, v3, 4, s[2:3]
	v_cndmask_b32_e64 v108, v3, 0, s[54:55]
	v_cndmask_b32_e64 v3, 13, 9, vcc
	v_cndmask_b32_e64 v3, v3, 5, s[2:3]
	v_cndmask_b32_e64 v110, v3, 1, s[54:55]
	v_cndmask_b32_e64 v3, 14, 10, vcc
	v_cndmask_b32_e64 v3, v3, 6, s[2:3]
	s_and_b64 s[72:73], s[40:41], s[38:39]
	v_cndmask_b32_e64 v112, v3, 2, s[54:55]
	v_cndmask_b32_e64 v3, 15, 11, vcc
	v_lshlrev_b32_e32 v1, 3, v2
	v_mul_u32_u24_e32 v4, 0x840, v190
	v_cndmask_b32_e64 v3, v3, 7, s[2:3]
	s_add_u32 s2, s58, s74
	s_mov_b64 s[16:17], s[24:25]
	v_add3_u32 v131, s92, v4, v5
	s_addc_u32 s3, s59, 0
	v_lshlrev_b32_e32 v4, 1, v1
	v_mov_b32_e32 v5, v193
	s_lshl_b32 s43, s43, 1
	s_mov_b64 s[20:21], s[28:29]
	v_lshl_add_u64 v[116:117], s[2:3], 0, v[4:5]
	s_add_u32 s2, s20, s43
	v_cndmask_b32_e64 v114, v3, 3, s[54:55]
	s_addc_u32 s3, s21, 0
	v_lshlrev_b32_e32 v2, 5, v2
	v_mov_b32_e32 v3, v193
	v_lshlrev_b32_e32 v6, 3, v6
	v_and_b32_e32 v7, 0x7f, v195
	v_mul_u32_u24_e32 v14, 0x50, v199
	v_mul_lo_u32 v20, v72, s11
	v_lshl_add_u64 v[118:119], s[2:3], 0, v[2:3]
	s_add_u32 s2, s58, s43
	v_lshl_add_u32 v13, v197, 5, s92
	v_lshlrev_b32_e32 v123, 4, v190
	v_lshl_add_u32 v125, v199, 1, s92
	v_lshlrev_b32_e32 v15, 5, v8
	v_lshlrev_b32_e32 v16, 1, v7
	v_mad_u32_u24 v7, v7, s11, v9
	v_lshl_add_u32 v19, v197, 1, s92
	v_add_u32_e32 v20, s92, v20
	v_mad_u32_u24 v9, v197, s11, v9
	v_add_u32_e32 v21, s92, v21
	v_or_b32_e32 v24, 0x80, v130
	v_or_b32_e32 v25, 0x100, v130
	v_or_b32_e32 v26, 0x180, v130
	v_add3_u32 v14, s92, v14, v198
	v_or_b32_e32 v27, 0x400, v130
	v_or_b32_e32 v28, 0x480, v130
	v_or_b32_e32 v29, 0x500, v130
	v_or_b32_e32 v30, 0x580, v130
	v_lshl_add_u32 v8, v8, 12, s92
	v_or_b32_e32 v56, 32, v198
	v_or_b32_e32 v57, 48, v198
	s_addc_u32 s3, s59, 0
	v_lshlrev_b32_e32 v2, 1, v6
	v_cvt_pk_bf16_f32 v52, v200, v201
	v_cvt_pk_bf16_f32 v53, v202, v203
	v_cvt_pk_bf16_f32 v54, v204, v205
	v_cvt_pk_bf16_f32 v55, v206, v207
	s_mov_b32 s10, 1
	v_add_u32_e32 v126, s92, v123
	s_mov_b32 s75, 6
	v_lshl_add_u32 v129, v199, 2, s92
	v_add_u32_e32 v133, 0x1080, v132
	v_add_u32_e32 v134, 0x2100, v132
	v_lshl_add_u64 v[120:121], s[2:3], 0, v[2:3]
	v_add_u32_e32 v135, v10, v192
	v_add_u32_e32 v136, v11, v0
	v_add_u32_e32 v137, v12, v0
	v_add_u32_e32 v138, v21, v22
	v_add_u32_e32 v139, v13, v123
	v_add_u32_e32 v140, v125, v23
	v_add_u32_e32 v141, v125, v24
	v_add_u32_e32 v142, v125, v25
	v_add_u32_e32 v143, v125, v26
	v_add_u32_e32 v144, v14, v15
	v_add_u32_e32 v145, v125, v27
	v_add_u32_e32 v146, v125, v28
	v_add_u32_e32 v147, v125, v29
	v_add_u32_e32 v148, v125, v30
	v_add_u32_e32 v149, v8, v16
	v_add_u32_e32 v150, v7, v15
	v_add_u32_e32 v151, v17, v123
	v_add_u32_e32 v152, v19, v31
	v_add_u32_e32 v153, v20, v123
	v_add_u32_e32 v154, v9, v123
	v_add_u32_e32 v155, v73, v18
	v_add_u32_e32 v156, v73, v56
	v_add_u32_e32 v157, v73, v57
	s_mov_b64 s[18:19], s[26:27]
	s_waitcnt vmcnt(0)
	s_branch .LBB0_635

.LBB0_635:
	s_waitcnt lgkmcnt(0)
	s_barrier
	s_waitcnt vmcnt(5)
	ds_write_b128 v135, v[32:35] offset:46848
	s_waitcnt vmcnt(4)
	ds_write_b128 v135, v[36:39] offset:50944
	s_waitcnt vmcnt(3)
	ds_write_b128 v136, v[40:43] offset:55040
	s_waitcnt vmcnt(2)
	ds_write_b128 v137, v[44:47] offset:55040
	s_and_saveexec_b64 s[2:3], s[0:1]
	ds_write_b128 v138, v[48:51] offset:24576
	s_or_b64 exec, exec, s[2:3]
	s_cmp_eq_u32 s75, -1
	s_cbranch_scc1 .LBB0_641
	s_and_b64 s[2:3], s[36:37], exec
	s_cselect_b32 s2, s75, s10
	s_lshl_b32 s43, s2, 5
	s_add_i32 s43, s43, s79
	v_add_u32_e32 v0, s43, v111
	v_mad_i64_i32 v[0:1], s[2:3], v0, s94, v[116:117]
	global_load_dwordx4 v[32:35], v[0:1], off offset:1024
	global_load_dwordx4 v[36:39], v[0:1], off offset:1536
	v_add_u32_e32 v0, s43, v113
	v_mad_i64_i32 v[0:1], s[2:3], v0, s94, v[120:121]
	v_add_u32_e32 v2, s43, v115
	v_mad_i64_i32 v[2:3], s[2:3], v2, s94, v[120:121]
	global_load_dwordx4 v[40:43], v[0:1], off offset:2048
	global_load_dwordx4 v[44:47], v[2:3], off offset:2048
	s_and_saveexec_b64 s[2:3], s[0:1]
	s_cbranch_execz .LBB0_640
	v_add_u32_e32 v2, s43, v122
	v_mov_b64_e32 v[0:1], s[58:59]
	v_mad_i64_i32 v[0:1], s[54:55], v2, s94, v[0:1]
	v_lshl_add_u64 v[0:1], v[106:107], 1, v[0:1]
	v_add_co_u32_e32 v0, vcc, 0x1000, v0
	s_nop 1
	v_addc_co_u32_e32 v1, vcc, 0, v1, vcc
	global_load_dwordx4 v[48:51], v[0:1], off

.LBB0_641:
	s_waitcnt lgkmcnt(0)
	s_barrier
	ds_read_b128 v[0:3], v139 offset:24576
	s_waitcnt lgkmcnt(0)
	v_mfma_f32_32x32x16_bf16 v[0:15], v[0:3], v[52:55], 0
	v_add_u32_e32 v211, v125, v130
	ds_read_u16 v212, v211 offset:50944
	ds_read_u16 v213, v211 offset:46848
	ds_read_u16 v214, v141 offset:50944
	ds_read_u16 v215, v141 offset:46848
	ds_read_u16 v216, v142 offset:50944
	ds_read_u16 v217, v142 offset:46848
	ds_read_u16 v218, v143 offset:50944
	ds_read_u16 v219, v143 offset:46848
	ds_read_u16 v220, v145 offset:50944
	ds_read_u16 v221, v145 offset:46848
	ds_read_u16 v222, v146 offset:50944
	ds_read_u16 v223, v146 offset:46848
	ds_read_u16 v224, v147 offset:50944
	ds_read_u16 v225, v147 offset:46848
	ds_read_u16 v226, v148 offset:50944
	ds_read_u16 v227, v148 offset:46848
	v_add_f32_e32 v16, v191, v0
	v_add_f32_e32 v17, v191, v1
	v_min_f32_e32 v0, 0, v16
	v_mul_f32_e64 v16, |v16|, s95
	v_min_f32_e32 v1, 0, v17
	v_mul_f32_e64 v17, |v17|, s95
	v_exp_f32_e32 v16, v16
	v_exp_f32_e32 v17, v17
	v_add_f32_e32 v2, v191, v2
	v_add_f32_e32 v22, v191, v3
	v_min_f32_e32 v3, 0, v2
	v_mul_f32_e64 v2, |v2|, s95
	v_add_f32_e32 v16, 1.0, v16
	v_add_f32_e32 v17, 1.0, v17
	v_mul_f32_e64 v18, |v22|, s95
	v_exp_f32_e32 v2, v2
	v_log_f32_e32 v16, v16
	v_log_f32_e32 v17, v17
	v_exp_f32_e32 v23, v18
	v_add_f32_e32 v4, v191, v4
	v_mul_f32_e64 v20, |v4|, s95
	v_add_f32_e32 v2, 1.0, v2
	v_pk_fma_f32 v[0:1], v[16:17], s[42:43], v[0:1] op_sel_hi:[1,0,1] neg_lo:[1,0,0] neg_hi:[1,0,0]
	v_exp_f32_e32 v16, v20
	v_log_f32_e32 v21, v2
	v_add_f32_e32 v2, 1.0, v23
	v_log_f32_e32 v20, v2
	v_add_f32_e32 v16, 1.0, v16
	v_min_f32_e32 v2, 0, v22
	v_log_f32_e32 v22, v16
	v_pk_fma_f32 v[2:3], v[20:21], s[42:43], v[2:3] op_sel_hi:[1,0,1] neg_lo:[1,0,0] neg_hi:[1,0,0]
	v_add_f32_e32 v20, v191, v5
	v_mul_f32_e64 v5, |v20|, s95
	v_add_f32_e32 v6, v191, v6
	v_min_f32_e32 v4, 0, v4
	v_exp_f32_e32 v21, v5
	v_mul_f32_e64 v5, |v6|, s95
	v_fmac_f32_e32 v4, 0xbf317218, v22
	v_exp_f32_e32 v22, v5
	v_mul_f32_e32 v5, 0x3d800000, v4
	v_add_f32_e32 v4, 1.0, v21
	v_log_f32_e32 v4, v4
	v_add_f32_e32 v21, 1.0, v22
	v_log_f32_e32 v21, v21
	v_min_f32_e32 v27, 0, v20
	v_fmac_f32_e32 v27, 0xbf317218, v4
	v_min_f32_e32 v4, 0, v6
	v_fmac_f32_e32 v4, 0xbf317218, v21
	v_mul_f32_e32 v195, 0x3d800000, v4
	v_add_f32_e32 v4, v191, v7
	v_min_f32_e32 v25, 0, v4
	v_mul_f32_e64 v4, |v4|, s95
	v_add_f32_e32 v6, v191, v8
	v_exp_f32_e32 v4, v4
	v_mul_f32_e64 v7, |v6|, s95
	v_exp_f32_e32 v7, v7
	v_min_f32_e32 v24, 0, v6
	v_add_f32_e32 v4, 1.0, v4
	v_log_f32_e32 v29, v4
	v_add_f32_e32 v4, 1.0, v7
	v_add_f32_e32 v6, v191, v9
	v_log_f32_e32 v28, v4
	v_min_f32_e32 v4, 0, v6
	v_mul_f32_e64 v6, |v6|, s95
	v_add_f32_e32 v7, v191, v10
	v_exp_f32_e32 v6, v6
	v_mul_f32_e64 v8, |v7|, s95
	v_exp_f32_e32 v8, v8
	v_pk_mul_f32 v[18:19], v[0:1], s[96:97] op_sel_hi:[1,0]
	v_add_f32_e32 v6, 1.0, v6
	v_log_f32_e32 v26, v6
	v_min_f32_e32 v6, 0, v7
	v_add_f32_e32 v7, 1.0, v8
	v_add_f32_e32 v8, v191, v11
	v_log_f32_e32 v7, v7
	v_mul_f32_e64 v9, |v8|, s95
	v_exp_f32_e32 v9, v9
	v_min_f32_e32 v30, 0, v8
	v_fmac_f32_e32 v6, 0xbf317218, v7
	v_mul_f32_e32 v20, 0x3d800000, v6
	v_add_f32_e32 v6, 1.0, v9
	v_add_f32_e32 v8, v191, v12
	v_add_f32_e32 v9, v191, v13
	v_mul_f32_e64 v7, |v8|, s95
	v_mul_f32_e64 v10, |v9|, s95
	v_log_f32_e32 v6, v6
	v_exp_f32_e32 v7, v7
	v_exp_f32_e32 v10, v10
	v_min_f32_e32 v8, 0, v8
	v_mul_f32_e32 v31, 0xbf317218, v6
	v_add_f32_e32 v6, 1.0, v7
	v_add_f32_e32 v7, 1.0, v10
	v_add_f32_e32 v10, v191, v14
	v_log_f32_e32 v6, v6
	v_log_f32_e32 v7, v7
	v_mul_f32_e64 v11, |v10|, s95
	v_exp_f32_e32 v11, v11
	v_min_f32_e32 v9, 0, v9
	v_pk_fma_f32 v[22:23], v[6:7], s[42:43], v[8:9] op_sel_hi:[1,0,1] neg_lo:[1,0,0] neg_hi:[1,0,0]
	v_add_f32_e32 v7, v191, v15
	v_add_f32_e32 v6, 1.0, v11
	v_mul_f32_e64 v8, |v7|, s95
	v_log_f32_e32 v6, v6
	v_exp_f32_e32 v11, v8
	v_min_f32_e32 v10, 0, v10
	v_pk_mul_f32 v[16:17], v[2:3], s[96:97] op_sel_hi:[1,0]
	v_fmac_f32_e32 v10, 0xbf317218, v6
	v_add_f32_e32 v6, 1.0, v11
	v_log_f32_e32 v11, v6
	v_pk_fma_f32 v[0:1], v[0:1], s[96:97], v[18:19] op_sel:[0,0,1] op_sel_hi:[1,0,0]
	v_mul_f32_e32 v6, 0x3d800000, v10
	v_pk_add_f32 v[0:1], v[16:17], v[0:1] op_sel:[1,0] op_sel_hi:[0,1]
	v_pk_fma_f32 v[2:3], v[2:3], s[96:97], v[0:1] op_sel_hi:[1,0,1]
	v_min_f32_e32 v0, 0, v7
	v_fmac_f32_e32 v0, 0xbf317218, v11
	v_pk_fma_f32 v[10:11], v[28:29], s[42:43], v[24:25] op_sel_hi:[1,0,1] neg_lo:[1,0,0] neg_hi:[1,0,0]
	s_mov_b32 s43, s96
	v_pk_fma_f32 v[12:13], v[26:27], s[42:43], v[4:5] neg_lo:[1,0,0] neg_hi:[1,0,0]
	v_pk_fma_f32 v[14:15], v[26:27], s[42:43], v[4:5]
	ds_bpermute_b32 v1, v124, v2
	v_mov_b32_e32 v13, v15
	v_pk_mul_f32 v[24:25], v[12:13], v[194:195]
	v_pk_add_f32 v[12:13], v[14:15], v[194:195]
	v_mul_f32_e32 v0, 0x3d800000, v0
	v_mov_b32_e32 v25, v13
	v_pk_fma_f32 v[12:13], v[10:11], s[96:97], v[24:25] op_sel_hi:[1,0,1]
	ds_bpermute_b32 v21, v124, v13
	s_waitcnt lgkmcnt(1)
	v_pk_add_f32 v[2:3], v[0:1], v[2:3] op_sel_hi:[1,0]
	v_add_f32_e32 v28, v30, v31
	v_mov_b32_e32 v29, v3
	v_pk_mul_f32 v[14:15], v[28:29], s[96:97]
	v_pk_add_f32 v[28:29], v[28:29], s[90:91]
	s_waitcnt lgkmcnt(0)
	v_pk_add_f32 v[2:3], v[12:13], v[20:21]
	v_mov_b32_e32 v15, v29
	v_pk_add_f32 v[12:13], v[14:15], v[2:3]
	v_add_f32_e32 v7, 0, v1
	ds_bpermute_b32 v1, v124, v12
	v_pk_mul_f32 v[2:3], v[10:11], s[96:97] op_sel_hi:[1,0]
	v_pk_mul_f32 v[10:11], v[26:27], s[42:43]
	v_cndmask_b32_e64 v7, v7, 0, s[38:39]
	v_pk_mul_f32 v[8:9], v[22:23], s[96:97] op_sel_hi:[1,0]
	s_waitcnt lgkmcnt(0)
	v_cndmask_b32_e64 v10, v1, 0, s[38:39]
	v_add_f32_e32 v1, v12, v1
	v_add_f32_e32 v10, v10, v13
	v_add_f32_e32 v12, v1, v13
	v_cndmask_b32_e64 v1, v2, v18, s[40:41]
	v_cndmask_b32_e64 v13, v10, v7, s[40:41]
	v_add_f32_e32 v7, 0, v1
	v_add_f32_e32 v10, v7, v13
	v_mul_f32_e32 v15, 0x3fb8aa3b, v10
	v_exp_f32_e32 v15, v15
	s_waitcnt lgkmcnt(1)
	v_lshlrev_b32_e32 v18, 16, v212
	v_mul_f32_e32 v2, 0xbfb8aa3b, v10
	s_waitcnt lgkmcnt(0)
	v_lshlrev_b32_e32 v1, 16, v213
	v_exp_f32_e32 v2, v2
	v_mul_f32_e32 v1, 0x3e000000, v1
	v_mul_f32_e32 v1, v1, v15
	v_cvt_pk_bf16_f32 v1, v1, s0
	ds_write_b16 v140, v1
	v_mul_f32_e32 v1, v2, v18
	v_cvt_pk_bf16_f32 v1, v1, s0
	v_cndmask_b32_e64 v4, v21, 0, s[38:39]
	v_cndmask_b32_e64 v15, v24, v19, s[40:41]
	ds_write_b16 v140, v1 offset:4608
	v_cndmask_b32_e64 v1, v20, v17, s[40:41]
	v_pk_fma_f32 v[20:21], v[22:23], s[96:97], v[8:9] op_sel:[0,0,1] op_sel_hi:[1,0,0]
	v_mov_b32_e32 v21, v15
	v_pk_add_f32 v[20:21], v[20:21], v[6:7]
	v_add_f32_e32 v4, v4, v29
	v_pk_add_f32 v[22:23], v[0:1], v[20:21]
	ds_bpermute_b32 v24, v124, v22
	s_waitcnt lgkmcnt(1)
	v_lshlrev_b32_e32 v1, 16, v215
	v_cndmask_b32_e64 v25, v14, v16, s[40:41]
	v_lshlrev_b32_e32 v19, 16, v214
	v_mul_f32_e32 v1, 0x3e000000, v1
	s_waitcnt lgkmcnt(0)
	v_pk_add_f32 v[14:15], v[22:23], v[24:25]
	v_cndmask_b32_e64 v2, v24, 0, s[38:39]
	v_pk_add_f32 v[14:15], v[14:15], v[12:13]
	v_add_f32_e32 v2, v2, v12
	v_sub_f32_e32 v7, v14, v10
	v_mul_f32_e32 v7, 0x3fb8aa3b, v7
	v_exp_f32_e32 v16, v7
	v_add_f32_e32 v7, v21, v13
	v_mul_f32_e32 v10, 0x3fb8aa3b, v7
	v_exp_f32_e32 v10, v10
	v_mul_f32_e32 v12, 0xbfb8aa3b, v7
	v_exp_f32_e32 v12, v12
	v_sub_f32_e32 v7, v14, v7
	v_mul_f32_e32 v1, v1, v10
	v_cvt_pk_bf16_f32 v1, v1, s0
	ds_write_b16 v140, v1 offset:144
	v_mul_f32_e32 v1, v12, v19
	v_cvt_pk_bf16_f32 v1, v1, s0
	v_mul_f32_e32 v7, 0x3fb8aa3b, v7
	ds_write_b16 v140, v1 offset:4752
	v_exp_f32_e32 v17, v7
	v_add_f32_e32 v10, v23, v13
	v_mul_f32_e32 v12, 0x3fb8aa3b, v10
	v_exp_f32_e32 v13, v12
	s_waitcnt lgkmcnt(1)
	v_lshlrev_b32_e32 v12, 16, v216
	s_waitcnt lgkmcnt(0)
	v_lshlrev_b32_e32 v1, 16, v217
	v_mul_f32_e32 v1, 0x3e000000, v1
	v_mul_f32_e32 v1, v1, v13
	v_cvt_pk_bf16_f32 v1, v1, s0
	ds_write_b16 v140, v1 offset:288
	v_mul_f32_e32 v1, 0xbfb8aa3b, v10
	v_exp_f32_e32 v1, v1
	v_sub_f32_e32 v7, v14, v10
	v_mul_f32_e32 v7, 0x3fb8aa3b, v7
	v_pk_mul_f32 v[16:17], v[16:17], v[18:19]
	v_mul_f32_e32 v1, v1, v12
	v_cvt_pk_bf16_f32 v1, v1, s0
	ds_write_b16 v140, v1 offset:4896
	v_exp_f32_e32 v18, v7
	v_mul_f32_e32 v7, 0x3fb8aa3b, v15
	v_exp_f32_e32 v7, v7
	v_sub_f32_e32 v13, v14, v15
	v_mul_f32_e32 v10, 0xbfb8aa3b, v15
	v_mul_f32_e32 v13, 0x3fb8aa3b, v13
	v_exp_f32_e32 v10, v10
	v_exp_f32_e32 v19, v13
	s_waitcnt lgkmcnt(1)
	v_lshlrev_b32_e32 v13, 16, v218
	s_waitcnt lgkmcnt(0)
	v_lshlrev_b32_e32 v1, 16, v219
	v_mul_f32_e32 v1, 0x3e000000, v1
	v_mul_f32_e32 v1, v7, v1
	v_cvt_pk_bf16_f32 v1, v1, s0
	ds_write_b16 v140, v1 offset:432
	v_mul_f32_e32 v1, v10, v13
	v_pk_mul_f32 v[12:13], v[18:19], v[12:13]
	v_cvt_pk_bf16_f32 v1, v1, s0
	v_cvt_pk_bf16_f32 v16, v16, v17
	v_cvt_pk_bf16_f32 v17, v12, v13
	ds_write_b16 v140, v1 offset:5040
	ds_write_b64 v144, v[16:17] offset:9216
	v_cndmask_b32_e64 v1, v8, v5, s[40:41]
	v_cndmask_b32_e64 v7, v2, v4, s[40:41]
	v_add_f32_e32 v1, 0, v1
	v_add_f32_e32 v8, v1, v7
	v_mul_f32_e32 v4, 0x3fb8aa3b, v8
	v_exp_f32_e32 v10, v4
	s_waitcnt lgkmcnt(1)
	v_lshlrev_b32_e32 v4, 16, v220
	s_waitcnt lgkmcnt(0)
	v_lshlrev_b32_e32 v2, 16, v221
	v_mul_f32_e32 v2, 0x3e000000, v2
	v_mul_f32_e32 v2, v10, v2
	v_cvt_pk_bf16_f32 v2, v2, s0
	ds_write_b16 v140, v2 offset:1152
	v_mul_f32_e32 v2, 0xbfb8aa3b, v8
	v_exp_f32_e32 v2, v2
	v_sub_f32_e32 v5, v14, v8
	v_mul_f32_e32 v5, 0x3fb8aa3b, v5
	v_exp_f32_e32 v8, v5
	v_mul_f32_e32 v2, v2, v4
	v_cvt_pk_bf16_f32 v2, v2, s0
	v_cndmask_b32_e64 v5, v9, v11, s[40:41]
	ds_write_b16 v140, v2 offset:5760
	v_add_f32_e32 v1, v5, v1
	v_add_f32_e32 v5, v1, v7
	v_mul_f32_e32 v9, 0x3fb8aa3b, v5
	v_exp_f32_e32 v10, v9
	v_mul_f32_e32 v9, 0xbfb8aa3b, v5
	v_sub_f32_e32 v5, v14, v5
	v_mul_f32_e32 v5, 0x3fb8aa3b, v5
	v_exp_f32_e32 v11, v9
	v_exp_f32_e32 v9, v5
	s_waitcnt lgkmcnt(1)
	v_lshlrev_b32_e32 v5, 16, v222
	s_waitcnt lgkmcnt(0)
	v_lshlrev_b32_e32 v2, 16, v223
	v_mul_f32_e32 v2, 0x3e000000, v2
	v_mul_f32_e32 v2, v10, v2
	v_cvt_pk_bf16_f32 v2, v2, s0
	ds_write_b16 v140, v2 offset:1296
	v_mul_f32_e32 v2, v11, v5
	v_cvt_pk_bf16_f32 v2, v2, s0
	ds_write_b16 v140, v2 offset:5904
	v_cndmask_b32_e64 v2, v6, v195, s[40:41]
	v_add_f32_e32 v1, v2, v1
	v_pk_mul_f32 v[4:5], v[8:9], v[4:5]
	v_add_f32_e32 v8, v1, v7
	v_mul_f32_e32 v9, 0x3fb8aa3b, v8
	v_exp_f32_e32 v9, v9
	s_waitcnt lgkmcnt(0)
	v_lshlrev_b32_e32 v6, 16, v225
	v_mul_f32_e32 v6, 0x3e000000, v6
	v_cndmask_b32_e64 v0, v0, v3, s[40:41]
	v_mul_f32_e32 v6, v9, v6
	v_cvt_pk_bf16_f32 v6, v6, s0
	ds_write_b16 v140, v6 offset:1440
	v_mul_f32_e32 v6, 0xbfb8aa3b, v8
	v_exp_f32_e32 v9, v6
	v_add_f32_e32 v0, v0, v1
	v_add_f32_e32 v0, v0, v7
	v_lshlrev_b32_e32 v2, 16, v224
	v_mul_f32_e32 v3, 0xbfb8aa3b, v0
	v_sub_f32_e32 v6, v14, v8
	v_exp_f32_e32 v8, v3
	v_mul_f32_e32 v3, v9, v2
	v_cvt_pk_bf16_f32 v3, v3, s0
	ds_write_b16 v140, v3 offset:6048
	v_mul_f32_e32 v1, 0x3fb8aa3b, v0
	v_exp_f32_e32 v1, v1
	v_sub_f32_e32 v0, v14, v0
	v_mul_f32_e32 v0, 0x3fb8aa3b, v0
	v_exp_f32_e32 v7, v0
	s_waitcnt lgkmcnt(0)
	v_lshlrev_b32_e32 v0, 16, v227
	v_mul_f32_e32 v6, 0x3fb8aa3b, v6
	v_mul_f32_e32 v0, 0x3e000000, v0
	v_exp_f32_e32 v6, v6
	v_mul_f32_e32 v0, v1, v0
	v_lshlrev_b32_e32 v3, 16, v226
	v_cvt_pk_bf16_f32 v0, v0, s0
	ds_write_b16 v140, v0 offset:1584
	v_mul_f32_e32 v0, v8, v3
	v_cvt_pk_bf16_f32 v0, v0, s0
	ds_write_b16 v140, v0 offset:6192
	v_pk_mul_f32 v[0:1], v[6:7], v[2:3]
	v_cvt_pk_bf16_f32 v2, v4, v5
	v_cvt_pk_bf16_f32 v3, v0, v1
	ds_write_b64 v144, v[2:3] offset:9232
	s_and_saveexec_b64 s[2:3], s[72:73]
	s_cbranch_execz .LBB0_634
	v_mul_f32_e32 v0, 0x3fb8aa3b, v14
	v_exp_f32_e32 v0, v0
	ds_write_b32 v129, v0 offset:45568
	s_branch .LBB0_634
